# grid barrier release: all WGs poll the top arrival counter directly (drops TOPGEN and per-XCD XGEN relay hops) at the 11 in-loop sites
# speedup vs baseline: 1.0078x; 1.0078x over previous
.LBB0_245:
	s_waitcnt lgkmcnt(0)
	v_readlane_b32 s4, v250, 17
	v_readlane_b32 s5, v250, 18
	s_lshl_b32 s2, s8, 8
	v_readfirstlane_b32 s7, v3
	v_readfirstlane_b32 s9, v2
	s_add_u32 s2, s4, s2
	s_addc_u32 s3, s5, 0
	s_add_u32 s4, s4, 0x3400
	s_addc_u32 s5, s5, 0
	v_mov_b32_e32 v4, 1
	v_mov_b32_e32 v5, 0x1000
	s_nop 4
	global_atomic_add v4, v5, v4, s[2:3] offset:1024 sc0
	s_mov_b32 s8, 0
	s_waitcnt vmcnt(0)
	v_readfirstlane_b32 s6, v4
	s_nop 1
XB_div_0:
	s_cmp_lt_u32 s6, s7
	s_cbranch_scc1 XB_divd_0
	s_sub_u32 s6, s6, s7
	s_add_u32 s8, s8, 1
	s_branch XB_div_0
XB_divd_0:
	s_add_u32 s8, s8, 1
	s_mul_i32 s9, s8, s9
	s_add_u32 s6, s6, 1
	s_cmp_lg_u32 s6, s7
	s_cbranch_scc1 XB_poll_0
	buffer_wbl2 sc1
	s_waitcnt vmcnt(0) lgkmcnt(0)
	v_mov_b32_e32 v4, 1
	s_nop 0
	global_atomic_add v1, v4, s[4:5]
XB_poll_0:
	global_load_dword v4, v1, s[4:5] sc1
	s_waitcnt vmcnt(0)
	v_readfirstlane_b32 s6, v4
	s_nop 1
	s_cmp_lt_u32 s6, s9
	s_cbranch_scc1 XB_poll_0
	buffer_inv sc1
	s_waitcnt vmcnt(0)
	s_branch .LBB0_282

XB_div_1:
	s_cmp_lt_u32 s6, s7
	s_cbranch_scc1 XB_divd_1
	s_sub_u32 s6, s6, s7
	s_add_u32 s8, s8, 1
	s_branch XB_div_1
XB_divd_1:
	s_add_u32 s8, s8, 1
	s_mul_i32 s9, s8, s9
	s_add_u32 s6, s6, 1
	s_cmp_lg_u32 s6, s7
	s_cbranch_scc1 XB_poll_1
	buffer_wbl2 sc1
	s_waitcnt vmcnt(0) lgkmcnt(0)
	v_mov_b32_e32 v4, 1
	s_nop 0
	global_atomic_add v1, v4, s[4:5]
XB_poll_1:
	global_load_dword v4, v1, s[4:5] sc1
	s_waitcnt vmcnt(0)
	v_readfirstlane_b32 s6, v4
	s_nop 1
	s_cmp_lt_u32 s6, s9
	s_cbranch_scc1 XB_poll_1
	buffer_inv sc1
	s_waitcnt vmcnt(0)
	s_branch .LBB0_1041

XB_div_2:
	s_cmp_lt_u32 s6, s7
	s_cbranch_scc1 XB_divd_2
	s_sub_u32 s6, s6, s7
	s_add_u32 s8, s8, 1
	s_branch XB_div_2
XB_divd_2:
	s_add_u32 s8, s8, 1
	s_mul_i32 s9, s8, s9
	s_add_u32 s6, s6, 1
	s_cmp_lg_u32 s6, s7
	s_cbranch_scc1 XB_poll_2
	buffer_wbl2 sc1
	s_waitcnt vmcnt(0) lgkmcnt(0)
	v_mov_b32_e32 v4, 1
	s_nop 0
	global_atomic_add v1, v4, s[4:5]
XB_poll_2:
	global_load_dword v4, v1, s[4:5] sc1
	s_waitcnt vmcnt(0)
	v_readfirstlane_b32 s6, v4
	s_nop 1
	s_cmp_lt_u32 s6, s9
	s_cbranch_scc1 XB_poll_2
	buffer_inv sc1
	s_waitcnt vmcnt(0)
	s_branch .LBB0_1120

XB_div_3:
	s_cmp_lt_u32 s6, s7
	s_cbranch_scc1 XB_divd_3
	s_sub_u32 s6, s6, s7
	s_add_u32 s8, s8, 1
	s_branch XB_div_3
XB_divd_3:
	s_add_u32 s8, s8, 1
	s_mul_i32 s9, s8, s9
	s_add_u32 s6, s6, 1
	s_cmp_lg_u32 s6, s7
	s_cbranch_scc1 XB_poll_3
	buffer_wbl2 sc1
	s_waitcnt vmcnt(0) lgkmcnt(0)
	v_mov_b32_e32 v4, 1
	s_nop 0
	global_atomic_add v1, v4, s[4:5]
XB_poll_3:
	global_load_dword v4, v1, s[4:5] sc1
	s_waitcnt vmcnt(0)
	v_readfirstlane_b32 s6, v4
	s_nop 1
	s_cmp_lt_u32 s6, s9
	s_cbranch_scc1 XB_poll_3
	buffer_inv sc1
	s_waitcnt vmcnt(0)
	s_branch .LBB0_1213

XB_div_4:
	s_cmp_lt_u32 s6, s7
	s_cbranch_scc1 XB_divd_4
	s_sub_u32 s6, s6, s7
	s_add_u32 s8, s8, 1
	s_branch XB_div_4
XB_divd_4:
	s_add_u32 s8, s8, 1
	s_mul_i32 s9, s8, s9
	s_add_u32 s6, s6, 1
	s_cmp_lg_u32 s6, s7
	s_cbranch_scc1 XB_poll_4
	buffer_wbl2 sc1
	s_waitcnt vmcnt(0) lgkmcnt(0)
	v_mov_b32_e32 v4, 1
	s_nop 0
	global_atomic_add v1, v4, s[4:5]
XB_poll_4:
	global_load_dword v4, v1, s[4:5] sc1
	s_waitcnt vmcnt(0)
	v_readfirstlane_b32 s6, v4
	s_nop 1
	s_cmp_lt_u32 s6, s9
	s_cbranch_scc1 XB_poll_4
	buffer_inv sc1
	s_waitcnt vmcnt(0)
	s_branch .LBB0_1346

XB_div_5:
	s_cmp_lt_u32 s6, s7
	s_cbranch_scc1 XB_divd_5
	s_sub_u32 s6, s6, s7
	s_add_u32 s8, s8, 1
	s_branch XB_div_5
XB_divd_5:
	s_add_u32 s8, s8, 1
	s_mul_i32 s9, s8, s9
	s_add_u32 s6, s6, 1
	s_cmp_lg_u32 s6, s7
	s_cbranch_scc1 XB_poll_5
	buffer_wbl2 sc1
	s_waitcnt vmcnt(0) lgkmcnt(0)
	v_mov_b32_e32 v4, 1
	s_nop 0
	global_atomic_add v1, v4, s[4:5]
XB_poll_5:
	global_load_dword v4, v1, s[4:5] sc1
	s_waitcnt vmcnt(0)
	v_readfirstlane_b32 s6, v4
	s_nop 1
	s_cmp_lt_u32 s6, s9
	s_cbranch_scc1 XB_poll_5
	buffer_inv sc1
	s_waitcnt vmcnt(0)
	s_branch .LBB0_1775

XB_div_6:
	s_cmp_lt_u32 s6, s7
	s_cbranch_scc1 XB_divd_6
	s_sub_u32 s6, s6, s7
	s_add_u32 s8, s8, 1
	s_branch XB_div_6
XB_divd_6:
	s_add_u32 s8, s8, 1
	s_mul_i32 s9, s8, s9
	s_add_u32 s6, s6, 1
	s_cmp_lg_u32 s6, s7
	s_cbranch_scc1 XB_poll_6
	buffer_wbl2 sc1
	s_waitcnt vmcnt(0) lgkmcnt(0)
	v_mov_b32_e32 v4, 1
	s_nop 0
	global_atomic_add v1, v4, s[4:5]
XB_poll_6:
	global_load_dword v4, v1, s[4:5] sc1
	s_waitcnt vmcnt(0)
	v_readfirstlane_b32 s6, v4
	s_nop 1
	s_cmp_lt_u32 s6, s9
	s_cbranch_scc1 XB_poll_6
	buffer_inv sc1
	s_waitcnt vmcnt(0)
	s_branch .LBB0_1505

XB_div_7:
	s_cmp_lt_u32 s6, s7
	s_cbranch_scc1 XB_divd_7
	s_sub_u32 s6, s6, s7
	s_add_u32 s8, s8, 1
	s_branch XB_div_7
XB_divd_7:
	s_add_u32 s8, s8, 1
	s_mul_i32 s9, s8, s9
	s_add_u32 s6, s6, 1
	s_cmp_lg_u32 s6, s7
	s_cbranch_scc1 XB_poll_7
	buffer_wbl2 sc1
	s_waitcnt vmcnt(0) lgkmcnt(0)
	v_mov_b32_e32 v4, 1
	s_nop 0
	global_atomic_add v1, v4, s[4:5]
XB_poll_7:
	global_load_dword v4, v1, s[4:5] sc1
	s_waitcnt vmcnt(0)
	v_readfirstlane_b32 s6, v4
	s_nop 1
	s_cmp_lt_u32 s6, s9
	s_cbranch_scc1 XB_poll_7
	buffer_inv sc1
	s_waitcnt vmcnt(0)
	s_branch .LBB0_1598

XB_div_8:
	s_cmp_lt_u32 s6, s7
	s_cbranch_scc1 XB_divd_8
	s_sub_u32 s6, s6, s7
	s_add_u32 s8, s8, 1
	s_branch XB_div_8
XB_divd_8:
	s_add_u32 s8, s8, 1
	s_mul_i32 s9, s8, s9
	s_add_u32 s6, s6, 1
	s_cmp_lg_u32 s6, s7
	s_cbranch_scc1 XB_poll_8
	buffer_wbl2 sc1
	s_waitcnt vmcnt(0) lgkmcnt(0)
	v_mov_b32_e32 v4, 1
	s_nop 0
	global_atomic_add v1, v4, s[4:5]
XB_poll_8:
	global_load_dword v4, v1, s[4:5] sc1
	s_waitcnt vmcnt(0)
	v_readfirstlane_b32 s6, v4
	s_nop 1
	s_cmp_lt_u32 s6, s9
	s_cbranch_scc1 XB_poll_8
	buffer_inv sc1
	s_waitcnt vmcnt(0)
	s_branch .LBB0_1675

XB_div_9:
	s_cmp_lt_u32 s6, s7
	s_cbranch_scc1 XB_divd_9
	s_sub_u32 s6, s6, s7
	s_add_u32 s8, s8, 1
	s_branch XB_div_9
XB_divd_9:
	s_add_u32 s8, s8, 1
	s_mul_i32 s9, s8, s9
	s_add_u32 s6, s6, 1
	s_cmp_lg_u32 s6, s7
	s_cbranch_scc1 XB_poll_9
	buffer_wbl2 sc1
	s_waitcnt vmcnt(0) lgkmcnt(0)
	v_mov_b32_e32 v4, 1
	s_nop 0
	global_atomic_add v1, v4, s[4:5]
XB_poll_9:
	global_load_dword v4, v1, s[4:5] sc1
	s_waitcnt vmcnt(0)
	v_readfirstlane_b32 s6, v4
	s_nop 1
	s_cmp_lt_u32 s6, s9
	s_cbranch_scc1 XB_poll_9
	buffer_inv sc1
	s_waitcnt vmcnt(0)
	s_mov_b64 s[4:5], exec
	s_branch .LBB0_1749

XB_div_10:
	s_cmp_lt_u32 s6, s7
	s_cbranch_scc1 XB_divd_10
	s_sub_u32 s6, s6, s7
	s_add_u32 s8, s8, 1
	s_branch XB_div_10
XB_divd_10:
	s_add_u32 s8, s8, 1
	s_mul_i32 s9, s8, s9
	s_add_u32 s6, s6, 1
	s_cmp_lg_u32 s6, s7
	s_cbranch_scc1 XB_poll_10
	buffer_wbl2 sc1
	s_waitcnt vmcnt(0) lgkmcnt(0)
	v_mov_b32_e32 v4, 1
	s_nop 0
	global_atomic_add v1, v4, s[4:5]
XB_poll_10:
	global_load_dword v4, v1, s[4:5] sc1
	s_waitcnt vmcnt(0)
	v_readfirstlane_b32 s6, v4
	s_nop 1
	s_cmp_lt_u32 s6, s9
	s_cbranch_scc1 XB_poll_10
	buffer_inv sc1
	s_waitcnt vmcnt(0)
	s_branch .LBB0_1868
